# prologue weight transposes: f32 weight loads marked nt (read-once stream)
# baseline (speedup 1.0000x reference)
; #define LAS __attribute__((address_space(3)))
; __device__ __forceinline__ unsigned pk2(float lo, float hi) { f32x2 v = {lo, hi}; bf16x2_t b = __builtin_convertvector(v, bf16x2_t); return __builtin_bit_cast(unsigned, b); }
; #define LDS_WAIT() asm volatile("s_waitcnt lgkmcnt(0)" ::: "memory")
; #define FIN(i) ((const float*)(const GAS float*)(((const float* const __attribute__((address_space(4)))*)__builtin_amdgcn_kernarg_segment_ptr())[i]))
; template <class MAP>
; __device__ __forceinline__ void transpose_item(const float* W, int ldw, int K, bf16_t* WT, int k0, int nd0, LAS float* scr, int lane, const MAP& map) {
;     const int nq = 4 * (lane & 15), ns = map(nd0 + nq), kr = lane >> 4;
;     f32x4 v[16];
; #pragma unroll
;     for (int i = 0; i < 16; ++i) v[i] = ns >= 0 ? *(const f32x4*)(W + (size_t)(k0 + 4 * i + kr) * ldw + ns) : (f32x4){0.f, 0.f, 0.f, 0.f};
; #pragma unroll
;     for (int i = 0; i < 16; ++i) { LAS float* d = scr + (4 * i + kr) * 65 + nq; d[0] = v[i].x; d[1] = v[i].y; d[2] = v[i].z; d[3] = v[i].w; }
;     LDS_WAIT(); asm volatile("" ::: "memory");
;     const int c = lane & 7;
; #pragma unroll
;     for (int j = 0; j < 8; ++j) { const int n = (lane >> 3) + 8 * j; const LAS float* s = scr + (8 * c) * 65 + n;
;         u32x4 o; o.x = pk2(s[0 * 65], s[1 * 65]); o.y = pk2(s[2 * 65], s[3 * 65]); o.z = pk2(s[4 * 65], s[5 * 65]); o.w = pk2(s[6 * 65], s[7 * 65]);
;         *(u32x4*)(WT + (size_t)(nd0 + n) * K + k0 + 8 * c) = o; }
;     LDS_WAIT(); asm volatile("" ::: "memory");
; __device__ __forceinline__ void phase_prologue(Frame& F) {
;     ...
;             transpose_item(FIN(IN_WPHI) + ((size_t)l * 128 + r) * 4096, 64, 64, (bf16_t*)(F.ws + WS_WPHI + l * al1m(SZ_WPHI)) + (size_t)r * 4096, 0, 0, scr, lane, MapId()); }
.LBB0_12:
	s_mul_hi_i32 s4, s61, 0x342da7f3
	s_lshr_b32 s5, s4, 31
	s_ashr_i32 s4, s4, 11
	s_add_i32 s8, s4, s5
	s_mul_i32 s4, s8, 0xffffd8c0
	s_add_i32 s10, s61, s4
	s_cmpk_gt_i32 s10, 0x1b7f
	s_mov_b64 s[4:5], -1
	s_cbranch_scc0 .LBB0_30
	s_cmpk_gt_u32 s10, 0x1c7f
	s_cbranch_scc0 .LBB0_27
	s_cmpk_gt_u32 s10, 0x227f
	s_cbranch_scc0 .LBB0_24
	s_cmpk_gt_u32 s10, 0x267f
	s_cbranch_scc0 .LBB0_21
	s_cmpk_gt_u32 s10, 0x26bf
	s_cbranch_scc0 .LBB0_18
	s_load_dwordx2 s[4:5], s[0:1], 0x68
	s_ashr_i32 s9, s8, 31
	s_add_i32 s6, s10, 0xffffd940
	s_lshl_b64 s[62:63], s[8:9], 21
	v_mov_b32_e32 v95, v73
	s_waitcnt lgkmcnt(0)
	s_add_u32 s11, s4, s62
	s_addc_u32 s62, s5, s63
	s_lshl_b64 s[4:5], s[6:7], 14
	s_add_u32 s4, s11, s4
	s_addc_u32 s5, s62, s5
	v_lshl_add_u64 v[2:3], s[4:5], 0, v[94:95]
	v_lshl_add_u64 v[50:51], v[2:3], 0, v[74:75]
	v_add_co_u32_e32 v46, vcc, s35, v50
	global_load_dwordx4 v[2:5], v[50:51], off nt
	global_load_dwordx4 v[6:9], v[50:51], off offset:1024 nt
	global_load_dwordx4 v[10:13], v[50:51], off offset:2048 nt
	global_load_dwordx4 v[14:17], v[50:51], off offset:3072 nt
	v_addc_co_u32_e32 v47, vcc, 0, v51, vcc
	v_add_co_u32_e32 v30, vcc, s34, v50
	global_load_dwordx4 v[18:21], v[46:47], off offset:-4096 nt
	s_nop 0
	v_addc_co_u32_e32 v31, vcc, 0, v51, vcc
	v_add_co_u32_e32 v62, vcc, s36, v50
	global_load_dwordx4 v[22:25], v[30:31], off offset:1024 nt
	global_load_dwordx4 v[26:29], v[30:31], off offset:2048 nt
	s_nop 0
	global_load_dwordx4 v[30:33], v[30:31], off offset:3072 nt
	s_nop 0
	global_load_dwordx4 v[34:37], v[46:47], off nt
	global_load_dwordx4 v[38:41], v[46:47], off offset:1024 nt
	global_load_dwordx4 v[42:45], v[46:47], off offset:2048 nt
	s_nop 0
	global_load_dwordx4 v[46:49], v[46:47], off offset:3072 nt
	v_addc_co_u32_e32 v63, vcc, 0, v51, vcc
	global_load_dwordx4 v[50:53], v[62:63], off nt
	global_load_dwordx4 v[54:57], v[62:63], off offset:1024 nt
	global_load_dwordx4 v[58:61], v[62:63], off offset:2048 nt
	s_nop 0
	global_load_dwordx4 v[62:65], v[62:63], off offset:3072 nt
	v_add_u32_e32 v95, 0x30c0, v69
	v_add_u32_e32 v96, 0x30c8, v69
	v_add_u32_e32 v97, 0x34d0, v69
	v_add_u32_e32 v142, 0x34d8, v69
	v_add_u32_e32 v143, 0x38e0, v69
	v_add_u32_e32 v144, 0x38e8, v69
	v_add_u32_e32 v145, 0x3cf0, v69
	v_add_u32_e32 v146, 0x3cf8, v69
	s_lshl_b64 s[4:5], s[8:9], 20
	v_add_u32_e32 v147, 0x400, v77
	s_add_u32 s9, s12, s4
	s_addc_u32 s11, s13, s5
	s_lshl_b64 s[4:5], s[6:7], 13
	s_add_u32 s4, s9, s4
	v_lshlrev_b32_e32 v72, 1, v76
	s_addc_u32 s5, s11, s5
	s_waitcnt vmcnt(15)
	ds_write2_b32 v69, v2, v3 offset1:1
	ds_write2_b32 v69, v4, v5 offset0:2 offset1:3
	s_waitcnt vmcnt(14)
	ds_write2_b32 v105, v6, v7 offset1:1
	ds_write2_b32 v106, v8, v9 offset1:1
	s_waitcnt vmcnt(13)
	ds_write2_b32 v107, v10, v11 offset1:1
	ds_write2_b32 v108, v12, v13 offset1:1
	s_waitcnt vmcnt(12)
	ds_write2_b32 v109, v14, v15 offset1:1
	ds_write2_b32 v110, v16, v17 offset1:1
	s_waitcnt vmcnt(11)
	ds_write2_b32 v111, v18, v19 offset1:1
	ds_write2_b32 v112, v20, v21 offset1:1
	s_waitcnt vmcnt(10)
	ds_write2_b32 v113, v22, v23 offset1:1
	ds_write2_b32 v114, v24, v25 offset1:1
	s_waitcnt vmcnt(9)
	ds_write2_b32 v115, v26, v27 offset1:1
	ds_write2_b32 v116, v28, v29 offset1:1
	s_waitcnt vmcnt(8)
	ds_write2_b32 v117, v30, v31 offset1:1
	ds_write2_b32 v118, v32, v33 offset1:1
	s_waitcnt vmcnt(7)
	ds_write2_b32 v119, v34, v35 offset1:1
	ds_write2_b32 v120, v36, v37 offset1:1
	s_waitcnt vmcnt(6)
	ds_write2_b32 v121, v38, v39 offset1:1
	ds_write2_b32 v122, v40, v41 offset1:1
	s_waitcnt vmcnt(5)
	ds_write2_b32 v123, v42, v43 offset1:1
	ds_write2_b32 v124, v44, v45 offset1:1
	s_waitcnt vmcnt(4)
	ds_write2_b32 v125, v46, v47 offset1:1
	ds_write2_b32 v126, v48, v49 offset1:1
	s_waitcnt vmcnt(3)
	ds_write2_b32 v95, v50, v51 offset1:1
	ds_write2_b32 v96, v52, v53 offset1:1
	s_waitcnt vmcnt(2)
	ds_write2_b32 v97, v54, v55 offset1:1
	ds_write2_b32 v142, v56, v57 offset1:1
	s_waitcnt vmcnt(1)
	ds_write2_b32 v143, v58, v59 offset1:1
	ds_write2_b32 v144, v60, v61 offset1:1
	s_waitcnt vmcnt(0)
	ds_write2_b32 v145, v62, v63 offset1:1
	ds_write2_b32 v146, v64, v65 offset1:1
	s_waitcnt lgkmcnt(0)
	ds_read2_b32 v[6:7], v77 offset0:65 offset1:73
	ds_read2_b32 v[8:9], v77 offset1:8
	ds_read2_b32 v[10:11], v77 offset0:130 offset1:138
	ds_read2_b32 v[12:13], v77 offset0:195 offset1:203
	ds_read2_b32 v[14:15], v147 offset0:4 offset1:12
	ds_read2_b32 v[16:17], v147 offset0:69 offset1:77
	ds_read2_b32 v[18:19], v147 offset0:134 offset1:142
	ds_read2_b32 v[20:21], v147 offset0:199 offset1:207
	v_lshl_add_u64 v[22:23], s[4:5], 0, v[72:73]
	s_waitcnt lgkmcnt(6)
	v_cvt_pk_bf16_f32 v2, v8, v6
	s_waitcnt lgkmcnt(4)
	v_cvt_pk_bf16_f32 v3, v10, v12
	s_waitcnt lgkmcnt(2)
	v_cvt_pk_bf16_f32 v4, v14, v16
	s_waitcnt lgkmcnt(0)
	v_cvt_pk_bf16_f32 v5, v18, v20
	v_lshl_add_u64 v[24:25], v[22:23], 0, v[78:79]
	global_store_dwordx4 v[24:25], v[2:5], off
	s_mov_b64 s[4:5], 0
	s_nop 0
	v_cvt_pk_bf16_f32 v2, v9, v7
	v_cvt_pk_bf16_f32 v3, v11, v13
	v_cvt_pk_bf16_f32 v4, v15, v17
	v_cvt_pk_bf16_f32 v5, v19, v21
	ds_read2_b32 v[8:9], v77 offset0:81 offset1:89
	ds_read2_b32 v[10:11], v77 offset0:16 offset1:24
	ds_read2_b32 v[12:13], v77 offset0:146 offset1:154
	ds_read2_b32 v[14:15], v77 offset0:211 offset1:219
	ds_read2_b32 v[16:17], v147 offset0:20 offset1:28
	ds_read2_b32 v[18:19], v147 offset0:85 offset1:93
	ds_read2_b32 v[20:21], v147 offset0:150 offset1:158
	ds_read2_b32 v[24:25], v147 offset0:215 offset1:223
	v_lshl_add_u64 v[6:7], v[22:23], 0, v[80:81]
	global_store_dwordx4 v[6:7], v[2:5], off
	v_lshl_add_u64 v[6:7], v[22:23], 0, v[82:83]
	s_waitcnt lgkmcnt(6)
	v_cvt_pk_bf16_f32 v2, v10, v8
	s_waitcnt lgkmcnt(4)
; #define LAS __attribute__((address_space(3)))
; __device__ __forceinline__ unsigned pk2(float lo, float hi) { f32x2 v = {lo, hi}; bf16x2_t b = __builtin_convertvector(v, bf16x2_t); return __builtin_bit_cast(unsigned, b); }
; template <class MAP>
; __device__ __forceinline__ void transpose_item(const float* W, int ldw, int K, bf16_t* WT, int k0, int nd0, LAS float* scr, int lane, const MAP& map) {
;     ...
;     for (int i = 0; i < 16; ++i) v[i] = ns >= 0 ? *(const f32x4*)(W + (size_t)(k0 + 4 * i + kr) * ldw + ns) : (f32x4){0.f, 0.f, 0.f, 0.f};
; #pragma unroll
;     for (int i = 0; i < 16; ++i) { LAS float* d = scr + (4 * i + kr) * 65 + nq; d[0] = v[i].x; d[1] = v[i].y; d[2] = v[i].z; d[3] = v[i].w; }
;     ...
;     for (int j = 0; j < 8; ++j) { const int n = (lane >> 3) + 8 * j; const LAS float* s = scr + (8 * c) * 65 + n;
;         u32x4 o; o.x = pk2(s[0 * 65], s[1 * 65]); o.y = pk2(s[2 * 65], s[3 * 65]); o.z = pk2(s[4 * 65], s[5 * 65]); o.w = pk2(s[6 * 65], s[7 * 65]);
;         *(u32x4*)(WT + (size_t)(nd0 + n) * K + k0 + 8 * c) = o; }
	v_cvt_pk_bf16_f32 v3, v12, v14
	s_waitcnt lgkmcnt(2)
	v_cvt_pk_bf16_f32 v4, v16, v18
	s_waitcnt lgkmcnt(0)
	v_cvt_pk_bf16_f32 v5, v20, v24
	global_store_dwordx4 v[6:7], v[2:5], off
	v_lshl_add_u64 v[6:7], v[22:23], 0, v[84:85]
	s_nop 0
	v_cvt_pk_bf16_f32 v2, v11, v9
	v_cvt_pk_bf16_f32 v3, v13, v15
	v_cvt_pk_bf16_f32 v4, v17, v19
	v_cvt_pk_bf16_f32 v5, v21, v25
	ds_read2_b32 v[8:9], v77 offset0:32 offset1:40
	ds_read2_b32 v[10:11], v77 offset0:97 offset1:105
	ds_read2_b32 v[12:13], v77 offset0:162 offset1:170
	ds_read2_b32 v[14:15], v77 offset0:227 offset1:235
	ds_read2_b32 v[16:17], v147 offset0:36 offset1:44
	ds_read2_b32 v[18:19], v147 offset0:101 offset1:109
	ds_read2_b32 v[20:21], v147 offset0:166 offset1:174
	ds_read2_b32 v[24:25], v147 offset0:231 offset1:239
	global_store_dwordx4 v[6:7], v[2:5], off
	v_lshl_add_u64 v[6:7], v[22:23], 0, v[86:87]
	s_waitcnt lgkmcnt(6)
	v_cvt_pk_bf16_f32 v2, v8, v10
	s_waitcnt lgkmcnt(4)
	v_cvt_pk_bf16_f32 v3, v12, v14
	s_waitcnt lgkmcnt(2)
	v_cvt_pk_bf16_f32 v4, v16, v18
	s_waitcnt lgkmcnt(0)
	v_cvt_pk_bf16_f32 v5, v20, v24
	global_store_dwordx4 v[6:7], v[2:5], off
	v_lshl_add_u64 v[6:7], v[22:23], 0, v[88:89]
	s_nop 0
	v_cvt_pk_bf16_f32 v2, v9, v11
	v_cvt_pk_bf16_f32 v3, v13, v15
	v_cvt_pk_bf16_f32 v4, v17, v19
	v_cvt_pk_bf16_f32 v5, v21, v25
	ds_read2_b32 v[8:9], v77 offset0:48 offset1:56
	ds_read2_b32 v[10:11], v77 offset0:113 offset1:121
	ds_read2_b32 v[12:13], v77 offset0:178 offset1:186
	ds_read2_b32 v[14:15], v77 offset0:243 offset1:251
	ds_read2_b32 v[16:17], v147 offset0:52 offset1:60
	ds_read2_b32 v[18:19], v147 offset0:117 offset1:125
	ds_read2_b32 v[20:21], v147 offset0:182 offset1:190
	ds_read2_b32 v[24:25], v147 offset0:247 offset1:255
	global_store_dwordx4 v[6:7], v[2:5], off
	v_lshl_add_u64 v[6:7], v[22:23], 0, v[90:91]
	s_waitcnt lgkmcnt(6)
	v_cvt_pk_bf16_f32 v2, v8, v10
	s_waitcnt lgkmcnt(4)
	v_cvt_pk_bf16_f32 v3, v12, v14
	s_waitcnt lgkmcnt(2)
	v_cvt_pk_bf16_f32 v4, v16, v18
	s_waitcnt lgkmcnt(0)
	v_cvt_pk_bf16_f32 v5, v20, v24
	global_store_dwordx4 v[6:7], v[2:5], off
	v_lshl_add_u64 v[6:7], v[22:23], 0, v[92:93]
	s_nop 0
	v_cvt_pk_bf16_f32 v2, v9, v11
	v_cvt_pk_bf16_f32 v3, v13, v15
	v_cvt_pk_bf16_f32 v4, v17, v19
	v_cvt_pk_bf16_f32 v5, v21, v25
	global_store_dwordx4 v[6:7], v[2:5], off
	s_waitcnt lgkmcnt(0)
.LBB0_18:
	s_andn2_b64 vcc, exec, s[4:5]
	s_cbranch_vccnz .LBB0_20
	s_load_dwordx2 s[4:5], s[0:1], 0x50
	s_add_i32 s6, s10, 0xffffd980
	s_ashr_i32 s9, s8, 31
	s_lshr_b32 s6, s6, 4
	s_lshl_b64 s[62:63], s[8:9], 20
	s_waitcnt lgkmcnt(0)
	s_add_u32 s9, s4, s62
	s_addc_u32 s11, s5, s63
	s_lshl_b64 s[4:5], s[6:7], 18
	s_add_u32 s64, s9, s4
	s_addc_u32 s65, s11, s5
	s_add_u32 s9, s15, s62
	s_addc_u32 s11, s16, s63
	s_lshl_b64 s[4:5], s[6:7], 17
	s_add_u32 s6, s9, s4
	s_addc_u32 s5, s11, s5
	s_and_b32 s4, s25, 0xc0
	s_and_b32 s9, s31, 0xc0
	v_or_b32_e32 v2, s4, v70
	v_or_b32_e32 v4, s9, v67
	v_lshlrev_b32_e32 v72, 2, v2
	v_lshl_add_u64 v[2:3], s[64:65], 0, v[72:73]
	v_lshlrev_b32_e32 v72, 10, v4
	v_lshl_add_u64 v[62:63], v[2:3], 0, v[72:73]
	v_add_co_u32_e32 v10, vcc, s35, v62
	global_load_dwordx4 v[2:5], v[62:63], off nt
	s_nop 0
	v_addc_co_u32_e32 v11, vcc, 0, v63, vcc
	v_add_co_u32_e32 v18, vcc, s37, v62
	global_load_dwordx4 v[6:9], v[10:11], off offset:-4096 nt
	s_nop 0
	global_load_dwordx4 v[10:13], v[10:11], off nt
	v_addc_co_u32_e32 v19, vcc, 0, v63, vcc
	v_add_co_u32_e32 v26, vcc, s38, v62
	global_load_dwordx4 v[14:17], v[18:19], off offset:-4096 nt
	s_nop 0
	global_load_dwordx4 v[18:21], v[18:19], off nt
	v_addc_co_u32_e32 v27, vcc, 0, v63, vcc
	v_add_co_u32_e32 v34, vcc, s39, v62
	global_load_dwordx4 v[22:25], v[26:27], off offset:-4096 nt
	s_nop 0
	global_load_dwordx4 v[26:29], v[26:27], off nt
	v_addc_co_u32_e32 v35, vcc, 0, v63, vcc
	v_add_co_u32_e32 v42, vcc, s40, v62
	global_load_dwordx4 v[30:33], v[34:35], off offset:-4096 nt
	s_nop 0
	global_load_dwordx4 v[34:37], v[34:35], off nt
	v_addc_co_u32_e32 v43, vcc, 0, v63, vcc
	v_add_co_u32_e32 v50, vcc, s41, v62
	global_load_dwordx4 v[38:41], v[42:43], off offset:-4096 nt
	s_nop 0
	global_load_dwordx4 v[42:45], v[42:43], off nt
	v_addc_co_u32_e32 v51, vcc, 0, v63, vcc
	global_load_dwordx4 v[46:49], v[50:51], off offset:-4096 nt
	s_nop 0
	global_load_dwordx4 v[50:53], v[50:51], off nt
	v_add_co_u32_e32 v58, vcc, s42, v62
	v_add_u32_e32 v72, 0x30c0, v69
	s_nop 0
	v_addc_co_u32_e32 v59, vcc, 0, v63, vcc
	global_load_dwordx4 v[54:57], v[58:59], off offset:-4096 nt
	s_nop 0
	global_load_dwordx4 v[58:61], v[58:59], off nt
	v_add_co_u32_e32 v62, vcc, s43, v62
	v_add_u32_e32 v95, 0x30c8, v69
	s_nop 0
	v_addc_co_u32_e32 v63, vcc, 0, v63, vcc
	global_load_dwordx4 v[62:65], v[62:63], off nt
	s_lshl_b32 s9, s9, 1
	s_add_u32 s62, s6, s9
	s_addc_u32 s63, s5, 0
	s_waitcnt vmcnt(15)
	ds_write2_b32 v69, v2, v3 offset1:1
	ds_write2_b32 v69, v4, v5 offset0:2 offset1:3
	s_waitcnt vmcnt(14)
	ds_write2_b32 v105, v6, v7 offset1:1
	ds_write2_b32 v106, v8, v9 offset1:1
	s_waitcnt vmcnt(13)
	ds_write2_b32 v107, v10, v11 offset1:1
	ds_write2_b32 v108, v12, v13 offset1:1
	s_waitcnt vmcnt(12)
	ds_write2_b32 v109, v14, v15 offset1:1
	ds_write2_b32 v110, v16, v17 offset1:1
	s_waitcnt vmcnt(11)
	ds_write2_b32 v111, v18, v19 offset1:1
	ds_write2_b32 v112, v20, v21 offset1:1
	s_waitcnt vmcnt(10)
	ds_write2_b32 v113, v22, v23 offset1:1
	ds_write2_b32 v114, v24, v25 offset1:1
	s_waitcnt vmcnt(9)
; #define LAS __attribute__((address_space(3)))
; __device__ __forceinline__ unsigned pk2(float lo, float hi) { f32x2 v = {lo, hi}; bf16x2_t b = __builtin_convertvector(v, bf16x2_t); return __builtin_bit_cast(unsigned, b); }
; #define LDS_WAIT() asm volatile("s_waitcnt lgkmcnt(0)" ::: "memory")
; template <class MAP>
; __device__ __forceinline__ void transpose_item(const float* W, int ldw, int K, bf16_t* WT, int k0, int nd0, LAS float* scr, int lane, const MAP& map) {
;     ...
;     for (int i = 0; i < 16; ++i) { LAS float* d = scr + (4 * i + kr) * 65 + nq; d[0] = v[i].x; d[1] = v[i].y; d[2] = v[i].z; d[3] = v[i].w; }
;     LDS_WAIT(); asm volatile("" ::: "memory");
;     const int c = lane & 7;
; #pragma unroll
;     for (int j = 0; j < 8; ++j) { const int n = (lane >> 3) + 8 * j; const LAS float* s = scr + (8 * c) * 65 + n;
;         u32x4 o; o.x = pk2(s[0 * 65], s[1 * 65]); o.y = pk2(s[2 * 65], s[3 * 65]); o.z = pk2(s[4 * 65], s[5 * 65]); o.w = pk2(s[6 * 65], s[7 * 65]);
;         *(u32x4*)(WT + (size_t)(nd0 + n) * K + k0 + 8 * c) = o; }
	ds_write2_b32 v115, v26, v27 offset1:1
	ds_write2_b32 v116, v28, v29 offset1:1
	s_waitcnt vmcnt(8)
	ds_write2_b32 v117, v30, v31 offset1:1
	ds_write2_b32 v118, v32, v33 offset1:1
	s_waitcnt vmcnt(7)
	ds_write2_b32 v119, v34, v35 offset1:1
	ds_write2_b32 v120, v36, v37 offset1:1
	s_waitcnt vmcnt(6)
	ds_write2_b32 v121, v38, v39 offset1:1
	ds_write2_b32 v122, v40, v41 offset1:1
	s_waitcnt vmcnt(5)
	ds_write2_b32 v123, v42, v43 offset1:1
	ds_write2_b32 v124, v44, v45 offset1:1
	s_waitcnt vmcnt(4)
	ds_write2_b32 v125, v46, v47 offset1:1
	ds_write2_b32 v126, v48, v49 offset1:1
	s_waitcnt vmcnt(3)
	ds_write2_b32 v72, v50, v51 offset1:1
	ds_write2_b32 v95, v52, v53 offset1:1
	v_add_u32_e32 v2, 0x34d0, v69
	v_add_u32_e32 v26, 0x400, v77
	v_lshlrev_b32_e32 v72, 1, v76
	v_lshl_add_u64 v[22:23], s[62:63], 0, v[72:73]
	s_waitcnt vmcnt(2)
	ds_write2_b32 v2, v54, v55 offset1:1
	v_add_u32_e32 v2, 0x34d8, v69
	ds_write2_b32 v2, v56, v57 offset1:1
	v_add_u32_e32 v2, 0x38e0, v69
	s_waitcnt vmcnt(1)
	ds_write2_b32 v2, v58, v59 offset1:1
	v_add_u32_e32 v2, 0x38e8, v69
	ds_write2_b32 v2, v60, v61 offset1:1
	v_add_u32_e32 v2, 0x3cf0, v69
	s_waitcnt vmcnt(0)
	ds_write2_b32 v2, v62, v63 offset1:1
	v_add_u32_e32 v2, 0x3cf8, v69
	ds_write2_b32 v2, v64, v65 offset1:1
	s_waitcnt lgkmcnt(0)
	ds_read2_b32 v[6:7], v77 offset0:65 offset1:73
	ds_read2_b32 v[8:9], v77 offset1:8
	ds_read2_b32 v[10:11], v77 offset0:130 offset1:138
	ds_read2_b32 v[12:13], v77 offset0:195 offset1:203
	ds_read2_b32 v[14:15], v26 offset0:4 offset1:12
	ds_read2_b32 v[16:17], v26 offset0:69 offset1:77
	ds_read2_b32 v[18:19], v26 offset0:134 offset1:142
	ds_read2_b32 v[20:21], v26 offset0:199 offset1:207
	s_waitcnt lgkmcnt(6)
	v_cvt_pk_bf16_f32 v2, v8, v6
	v_or_b32_e32 v6, s4, v71
	v_lshlrev_b32_e32 v72, 9, v6
	s_waitcnt lgkmcnt(4)
	v_cvt_pk_bf16_f32 v3, v10, v12
	s_waitcnt lgkmcnt(2)
	v_cvt_pk_bf16_f32 v4, v14, v16
	s_waitcnt lgkmcnt(0)
	v_cvt_pk_bf16_f32 v5, v18, v20
	v_lshl_add_u64 v[24:25], v[22:23], 0, v[72:73]
	global_store_dwordx4 v[24:25], v[2:5], off
	v_or_b32_e32 v6, s4, v98
	v_lshlrev_b32_e32 v72, 9, v6
	v_cvt_pk_bf16_f32 v2, v9, v7
	v_cvt_pk_bf16_f32 v3, v11, v13
	v_cvt_pk_bf16_f32 v4, v15, v17
	v_cvt_pk_bf16_f32 v5, v19, v21
	ds_read2_b32 v[8:9], v77 offset0:81 offset1:89
	ds_read2_b32 v[10:11], v77 offset0:16 offset1:24
	ds_read2_b32 v[12:13], v77 offset0:146 offset1:154
	ds_read2_b32 v[14:15], v77 offset0:211 offset1:219
	ds_read2_b32 v[16:17], v26 offset0:20 offset1:28
	ds_read2_b32 v[18:19], v26 offset0:85 offset1:93
	ds_read2_b32 v[20:21], v26 offset0:150 offset1:158
	ds_read2_b32 v[24:25], v26 offset0:215 offset1:223
	v_lshl_add_u64 v[6:7], v[22:23], 0, v[72:73]
	global_store_dwordx4 v[6:7], v[2:5], off
	v_or_b32_e32 v6, s4, v99
	v_lshlrev_b32_e32 v72, 9, v6
	s_waitcnt lgkmcnt(6)
	v_cvt_pk_bf16_f32 v2, v10, v8
	s_waitcnt lgkmcnt(4)
	v_cvt_pk_bf16_f32 v3, v12, v14
	s_waitcnt lgkmcnt(2)
	v_cvt_pk_bf16_f32 v4, v16, v18
	s_waitcnt lgkmcnt(0)
	v_cvt_pk_bf16_f32 v5, v20, v24
	v_lshl_add_u64 v[6:7], v[22:23], 0, v[72:73]
	global_store_dwordx4 v[6:7], v[2:5], off
	v_or_b32_e32 v6, s4, v100
	v_lshlrev_b32_e32 v72, 9, v6
	v_cvt_pk_bf16_f32 v2, v11, v9
	v_cvt_pk_bf16_f32 v3, v13, v15
	v_cvt_pk_bf16_f32 v4, v17, v19
	v_cvt_pk_bf16_f32 v5, v21, v25
	ds_read2_b32 v[8:9], v77 offset0:32 offset1:40
	ds_read2_b32 v[10:11], v77 offset0:97 offset1:105
	ds_read2_b32 v[12:13], v77 offset0:162 offset1:170
	ds_read2_b32 v[14:15], v77 offset0:227 offset1:235
	ds_read2_b32 v[16:17], v26 offset0:36 offset1:44
	ds_read2_b32 v[18:19], v26 offset0:101 offset1:109
	ds_read2_b32 v[20:21], v26 offset0:166 offset1:174
	ds_read2_b32 v[24:25], v26 offset0:231 offset1:239
	v_lshl_add_u64 v[6:7], v[22:23], 0, v[72:73]
	global_store_dwordx4 v[6:7], v[2:5], off
	v_or_b32_e32 v6, s4, v101
	v_lshlrev_b32_e32 v72, 9, v6
	s_waitcnt lgkmcnt(6)
	v_cvt_pk_bf16_f32 v2, v8, v10
	s_waitcnt lgkmcnt(4)
	v_cvt_pk_bf16_f32 v3, v12, v14
	s_waitcnt lgkmcnt(2)
	v_cvt_pk_bf16_f32 v4, v16, v18
	s_waitcnt lgkmcnt(0)
	v_cvt_pk_bf16_f32 v5, v20, v24
	v_lshl_add_u64 v[6:7], v[22:23], 0, v[72:73]
	global_store_dwordx4 v[6:7], v[2:5], off
	v_or_b32_e32 v6, s4, v102
	v_lshlrev_b32_e32 v72, 9, v6
	v_cvt_pk_bf16_f32 v2, v9, v11
	v_cvt_pk_bf16_f32 v3, v13, v15
	v_cvt_pk_bf16_f32 v4, v17, v19
	v_cvt_pk_bf16_f32 v5, v21, v25
	ds_read2_b32 v[8:9], v77 offset0:48 offset1:56
	ds_read2_b32 v[10:11], v77 offset0:113 offset1:121
	ds_read2_b32 v[12:13], v77 offset0:178 offset1:186
	ds_read2_b32 v[14:15], v77 offset0:243 offset1:251
	ds_read2_b32 v[16:17], v26 offset0:52 offset1:60
	ds_read2_b32 v[18:19], v26 offset0:117 offset1:125
	ds_read2_b32 v[20:21], v26 offset0:182 offset1:190
	ds_read2_b32 v[24:25], v26 offset0:247 offset1:255
	v_lshl_add_u64 v[6:7], v[22:23], 0, v[72:73]
	global_store_dwordx4 v[6:7], v[2:5], off
	v_or_b32_e32 v6, s4, v103
	v_lshlrev_b32_e32 v72, 9, v6
	s_waitcnt lgkmcnt(6)
	v_cvt_pk_bf16_f32 v2, v8, v10
	s_waitcnt lgkmcnt(4)
	v_cvt_pk_bf16_f32 v3, v12, v14
	s_waitcnt lgkmcnt(2)
	v_cvt_pk_bf16_f32 v4, v16, v18
	s_waitcnt lgkmcnt(0)
	v_cvt_pk_bf16_f32 v5, v20, v24
	v_lshl_add_u64 v[6:7], v[22:23], 0, v[72:73]
	global_store_dwordx4 v[6:7], v[2:5], off
	v_or_b32_e32 v6, s4, v104
	v_lshlrev_b32_e32 v72, 9, v6
	v_cvt_pk_bf16_f32 v2, v9, v11
	v_cvt_pk_bf16_f32 v3, v13, v15
	v_cvt_pk_bf16_f32 v4, v17, v19
	v_cvt_pk_bf16_f32 v5, v21, v25
	v_lshl_add_u64 v[6:7], v[22:23], 0, v[72:73]
	global_store_dwordx4 v[6:7], v[2:5], off
	s_waitcnt lgkmcnt(0)

; #define LAS __attribute__((address_space(3)))
; #define FIN(i) ((const float*)(const GAS float*)(((const float* const __attribute__((address_space(4)))*)__builtin_amdgcn_kernarg_segment_ptr())[i]))
; template <class MAP>
; __device__ __forceinline__ void transpose_item(const float* W, int ldw, int K, bf16_t* WT, int k0, int nd0, LAS float* scr, int lane, const MAP& map) {
;     ...
;     for (int i = 0; i < 16; ++i) v[i] = ns >= 0 ? *(const f32x4*)(W + (size_t)(k0 + 4 * i + kr) * ldw + ns) : (f32x4){0.f, 0.f, 0.f, 0.f};
; #pragma unroll
;     for (int i = 0; i < 16; ++i) { LAS float* d = scr + (4 * i + kr) * 65 + nq; d[0] = v[i].x; d[1] = v[i].y; d[2] = v[i].z; d[3] = v[i].w; }
; __device__ __forceinline__ void phase_prologue(Frame& F) {
;     ...
;             transpose_item(FIN(IN_WOUT) + (size_t)l * 2048 * 2048, 2048, 2048, (bf16_t*)(F.ws + WS_WOUT + l * al1m(SZ_WOUT)), 64 * kb, 64 * nb, scr, lane, MapId()); continue; } r -= I_OUT;
.LBB0_21:
	s_andn2_b64 vcc, exec, s[4:5]
	s_cbranch_vccnz .LBB0_23
	s_load_dwordx2 s[4:5], s[0:1], 0xd0
	s_ashr_i32 s9, s8, 31
	s_lshl_b64 s[62:63], s[8:9], 24
	s_mul_i32 s6, s8, 0xffffb180
	v_mov_b32_e32 v63, v73
	s_waitcnt lgkmcnt(0)
	s_add_u32 s62, s4, s62
	s_addc_u32 s63, s5, s63
	s_lshl_b64 s[4:5], s[8:9], 23
	s_add_u32 s9, s17, s4
	s_addc_u32 s5, s18, s5
	s_add_i32 s4, s29, s6
	s_and_b32 s4, s4, 0x7fc0
	s_add_i32 s6, s4, 0xffffbb00
	s_and_b32 s4, s25, 0x7c0
	v_or_b32_e32 v2, s4, v70
	v_or_b32_e32 v62, s6, v67
	v_lshlrev_b32_e32 v72, 2, v2
	v_lshl_add_u64 v[64:65], s[62:63], 0, v[72:73]
	v_or_b32_e32 v72, 4, v62
	v_lshlrev_b64 v[4:5], 13, v[72:73]
	v_or_b32_e32 v72, 8, v62
	v_lshlrev_b64 v[10:11], 13, v[72:73]
	v_or_b32_e32 v72, 12, v62
	v_lshlrev_b64 v[12:13], 13, v[72:73]
	v_or_b32_e32 v72, 16, v62
	v_lshlrev_b64 v[18:19], 13, v[72:73]
	v_or_b32_e32 v72, 20, v62
	v_lshlrev_b64 v[20:21], 13, v[72:73]
	v_or_b32_e32 v72, 24, v62
	v_lshlrev_b64 v[26:27], 13, v[72:73]
	v_or_b32_e32 v72, 28, v62
	v_lshlrev_b64 v[28:29], 13, v[72:73]
	v_or_b32_e32 v72, 32, v62
	v_lshlrev_b64 v[34:35], 13, v[72:73]
	v_or_b32_e32 v72, 36, v62
	v_lshlrev_b64 v[36:37], 13, v[72:73]
	v_or_b32_e32 v72, 40, v62
	v_lshlrev_b64 v[42:43], 13, v[72:73]
	v_or_b32_e32 v72, 44, v62
	v_lshlrev_b64 v[2:3], 13, v[62:63]
	v_lshlrev_b64 v[44:45], 13, v[72:73]
	v_or_b32_e32 v72, 48, v62
	v_lshl_add_u64 v[2:3], v[64:65], 0, v[2:3]
	v_lshl_add_u64 v[6:7], v[64:65], 0, v[4:5]
	v_lshl_add_u64 v[10:11], v[64:65], 0, v[10:11]
	v_lshl_add_u64 v[14:15], v[64:65], 0, v[12:13]
	v_lshl_add_u64 v[18:19], v[64:65], 0, v[18:19]
	v_lshl_add_u64 v[22:23], v[64:65], 0, v[20:21]
	v_lshl_add_u64 v[26:27], v[64:65], 0, v[26:27]
	v_lshl_add_u64 v[30:31], v[64:65], 0, v[28:29]
	v_lshl_add_u64 v[34:35], v[64:65], 0, v[34:35]
	v_lshl_add_u64 v[38:39], v[64:65], 0, v[36:37]
	v_lshl_add_u64 v[42:43], v[64:65], 0, v[42:43]
	v_lshl_add_u64 v[46:47], v[64:65], 0, v[44:45]
	v_lshlrev_b64 v[50:51], 13, v[72:73]
	v_or_b32_e32 v72, 52, v62
	global_load_dwordx4 v[2:5], v[2:3], off nt
	s_nop 0
	global_load_dwordx4 v[6:9], v[6:7], off nt
	s_nop 0
	global_load_dwordx4 v[10:13], v[10:11], off nt
	s_nop 0
	global_load_dwordx4 v[14:17], v[14:15], off nt
	s_nop 0
	global_load_dwordx4 v[18:21], v[18:19], off nt
	s_nop 0
	global_load_dwordx4 v[22:25], v[22:23], off nt
	s_nop 0
	global_load_dwordx4 v[26:29], v[26:27], off nt
	s_nop 0
	global_load_dwordx4 v[30:33], v[30:31], off nt
	s_nop 0
	global_load_dwordx4 v[34:37], v[34:35], off nt
	s_nop 0
	global_load_dwordx4 v[38:41], v[38:39], off nt
	s_nop 0
	global_load_dwordx4 v[42:45], v[42:43], off nt
	s_nop 0
	global_load_dwordx4 v[46:49], v[46:47], off nt
	v_lshl_add_u64 v[50:51], v[64:65], 0, v[50:51]
	v_lshlrev_b64 v[54:55], 13, v[72:73]
	global_load_dwordx4 v[50:53], v[50:51], off nt
	v_lshl_add_u64 v[54:55], v[64:65], 0, v[54:55]
	v_or_b32_e32 v72, 56, v62
	global_load_dwordx4 v[54:57], v[54:55], off nt
	v_lshlrev_b64 v[58:59], 13, v[72:73]
	v_lshl_add_u64 v[58:59], v[64:65], 0, v[58:59]
	v_or_b32_e32 v72, 60, v62
	global_load_dwordx4 v[58:61], v[58:59], off nt
	v_lshlrev_b64 v[62:63], 13, v[72:73]
	v_lshl_add_u64 v[62:63], v[64:65], 0, v[62:63]
	global_load_dwordx4 v[62:65], v[62:63], off nt
	v_add_u32_e32 v72, 0x30c0, v69
	s_lshl_b64 s[62:63], s[6:7], 1
	s_add_u32 s62, s9, s62
	s_addc_u32 s63, s5, s63
	s_waitcnt vmcnt(15)
	ds_write2_b32 v69, v2, v3 offset1:1
	ds_write2_b32 v69, v4, v5 offset0:2 offset1:3
	s_waitcnt vmcnt(14)
	ds_write2_b32 v105, v6, v7 offset1:1
	ds_write2_b32 v106, v8, v9 offset1:1
	s_waitcnt vmcnt(13)
	ds_write2_b32 v107, v10, v11 offset1:1
	ds_write2_b32 v108, v12, v13 offset1:1
	s_waitcnt vmcnt(12)
	ds_write2_b32 v109, v14, v15 offset1:1
	ds_write2_b32 v110, v16, v17 offset1:1
	s_waitcnt vmcnt(11)
	ds_write2_b32 v111, v18, v19 offset1:1
	ds_write2_b32 v112, v20, v21 offset1:1
	s_waitcnt vmcnt(10)
	ds_write2_b32 v113, v22, v23 offset1:1
	ds_write2_b32 v114, v24, v25 offset1:1
	s_waitcnt vmcnt(9)
	ds_write2_b32 v115, v26, v27 offset1:1
	ds_write2_b32 v116, v28, v29 offset1:1
	s_waitcnt vmcnt(8)
	ds_write2_b32 v117, v30, v31 offset1:1
	ds_write2_b32 v118, v32, v33 offset1:1
	s_waitcnt vmcnt(7)
	ds_write2_b32 v119, v34, v35 offset1:1
	ds_write2_b32 v120, v36, v37 offset1:1
	s_waitcnt vmcnt(6)
	ds_write2_b32 v121, v38, v39 offset1:1
	ds_write2_b32 v122, v40, v41 offset1:1
	s_waitcnt vmcnt(5)
	ds_write2_b32 v123, v42, v43 offset1:1
	ds_write2_b32 v124, v44, v45 offset1:1
	s_waitcnt vmcnt(4)
	ds_write2_b32 v125, v46, v47 offset1:1
	ds_write2_b32 v126, v48, v49 offset1:1
	s_waitcnt vmcnt(3)
	ds_write2_b32 v72, v50, v51 offset1:1
	v_add_u32_e32 v2, 0x30c8, v69
	v_add_u32_e32 v26, 0x400, v77
	ds_write2_b32 v2, v52, v53 offset1:1
	v_add_u32_e32 v2, 0x34d0, v69
	v_lshlrev_b32_e32 v72, 1, v76
	s_waitcnt vmcnt(2)
; #define LAS __attribute__((address_space(3)))
; __device__ __forceinline__ unsigned pk2(float lo, float hi) { f32x2 v = {lo, hi}; bf16x2_t b = __builtin_convertvector(v, bf16x2_t); return __builtin_bit_cast(unsigned, b); }
; #define LDS_WAIT() asm volatile("s_waitcnt lgkmcnt(0)" ::: "memory")
; template <class MAP>
; __device__ __forceinline__ void transpose_item(const float* W, int ldw, int K, bf16_t* WT, int k0, int nd0, LAS float* scr, int lane, const MAP& map) {
;     ...
;     for (int i = 0; i < 16; ++i) { LAS float* d = scr + (4 * i + kr) * 65 + nq; d[0] = v[i].x; d[1] = v[i].y; d[2] = v[i].z; d[3] = v[i].w; }
;     LDS_WAIT(); asm volatile("" ::: "memory");
;     const int c = lane & 7;
; #pragma unroll
;     for (int j = 0; j < 8; ++j) { const int n = (lane >> 3) + 8 * j; const LAS float* s = scr + (8 * c) * 65 + n;
;         u32x4 o; o.x = pk2(s[0 * 65], s[1 * 65]); o.y = pk2(s[2 * 65], s[3 * 65]); o.z = pk2(s[4 * 65], s[5 * 65]); o.w = pk2(s[6 * 65], s[7 * 65]);
;         *(u32x4*)(WT + (size_t)(nd0 + n) * K + k0 + 8 * c) = o; }
;     LDS_WAIT(); asm volatile("" ::: "memory");
	ds_write2_b32 v2, v54, v55 offset1:1
	v_add_u32_e32 v2, 0x34d8, v69
	ds_write2_b32 v2, v56, v57 offset1:1
	v_add_u32_e32 v2, 0x38e0, v69
	s_waitcnt vmcnt(1)
	ds_write2_b32 v2, v58, v59 offset1:1
	v_add_u32_e32 v2, 0x38e8, v69
	ds_write2_b32 v2, v60, v61 offset1:1
	v_add_u32_e32 v2, 0x3cf0, v69
	s_waitcnt vmcnt(0)
	ds_write2_b32 v2, v62, v63 offset1:1
	v_add_u32_e32 v2, 0x3cf8, v69
	ds_write2_b32 v2, v64, v65 offset1:1
	s_waitcnt lgkmcnt(0)
	ds_read2_b32 v[6:7], v77 offset0:65 offset1:73
	ds_read2_b32 v[8:9], v77 offset1:8
	ds_read2_b32 v[10:11], v77 offset0:130 offset1:138
	ds_read2_b32 v[12:13], v77 offset0:195 offset1:203
	ds_read2_b32 v[14:15], v26 offset0:4 offset1:12
	ds_read2_b32 v[16:17], v26 offset0:69 offset1:77
	ds_read2_b32 v[18:19], v26 offset0:134 offset1:142
	ds_read2_b32 v[20:21], v26 offset0:199 offset1:207
	v_lshl_add_u64 v[22:23], s[62:63], 0, v[72:73]
	s_waitcnt lgkmcnt(6)
	v_cvt_pk_bf16_f32 v2, v8, v6
	v_or_b32_e32 v6, s4, v71
	v_lshlrev_b32_e32 v72, 12, v6
	s_waitcnt lgkmcnt(4)
	v_cvt_pk_bf16_f32 v3, v10, v12
	s_waitcnt lgkmcnt(2)
	v_cvt_pk_bf16_f32 v4, v14, v16
	s_waitcnt lgkmcnt(0)
	v_cvt_pk_bf16_f32 v5, v18, v20
	v_lshl_add_u64 v[24:25], v[22:23], 0, v[72:73]
	global_store_dwordx4 v[24:25], v[2:5], off
	v_or_b32_e32 v6, s4, v98
	v_lshlrev_b32_e32 v72, 12, v6
	v_cvt_pk_bf16_f32 v2, v9, v7
	v_cvt_pk_bf16_f32 v3, v11, v13
	v_cvt_pk_bf16_f32 v4, v15, v17
	v_cvt_pk_bf16_f32 v5, v19, v21
	ds_read2_b32 v[8:9], v77 offset0:81 offset1:89
	ds_read2_b32 v[10:11], v77 offset0:16 offset1:24
	ds_read2_b32 v[12:13], v77 offset0:146 offset1:154
	ds_read2_b32 v[14:15], v77 offset0:211 offset1:219
	ds_read2_b32 v[16:17], v26 offset0:20 offset1:28
	ds_read2_b32 v[18:19], v26 offset0:85 offset1:93
	ds_read2_b32 v[20:21], v26 offset0:150 offset1:158
	ds_read2_b32 v[24:25], v26 offset0:215 offset1:223
	v_lshl_add_u64 v[6:7], v[22:23], 0, v[72:73]
	global_store_dwordx4 v[6:7], v[2:5], off
	v_or_b32_e32 v6, s4, v99
	v_lshlrev_b32_e32 v72, 12, v6
	s_waitcnt lgkmcnt(6)
	v_cvt_pk_bf16_f32 v2, v10, v8
	s_waitcnt lgkmcnt(4)
	v_cvt_pk_bf16_f32 v3, v12, v14
	s_waitcnt lgkmcnt(2)
	v_cvt_pk_bf16_f32 v4, v16, v18
	s_waitcnt lgkmcnt(0)
	v_cvt_pk_bf16_f32 v5, v20, v24
	v_lshl_add_u64 v[6:7], v[22:23], 0, v[72:73]
	global_store_dwordx4 v[6:7], v[2:5], off
	v_or_b32_e32 v6, s4, v100
	v_lshlrev_b32_e32 v72, 12, v6
	v_cvt_pk_bf16_f32 v2, v11, v9
	v_cvt_pk_bf16_f32 v3, v13, v15
	v_cvt_pk_bf16_f32 v4, v17, v19
	v_cvt_pk_bf16_f32 v5, v21, v25
	ds_read2_b32 v[8:9], v77 offset0:32 offset1:40
	ds_read2_b32 v[10:11], v77 offset0:97 offset1:105
	ds_read2_b32 v[12:13], v77 offset0:162 offset1:170
	ds_read2_b32 v[14:15], v77 offset0:227 offset1:235
	ds_read2_b32 v[16:17], v26 offset0:36 offset1:44
	ds_read2_b32 v[18:19], v26 offset0:101 offset1:109
	ds_read2_b32 v[20:21], v26 offset0:166 offset1:174
	ds_read2_b32 v[24:25], v26 offset0:231 offset1:239
	v_lshl_add_u64 v[6:7], v[22:23], 0, v[72:73]
	global_store_dwordx4 v[6:7], v[2:5], off
	v_or_b32_e32 v6, s4, v101
	v_lshlrev_b32_e32 v72, 12, v6
	s_waitcnt lgkmcnt(6)
	v_cvt_pk_bf16_f32 v2, v8, v10
	s_waitcnt lgkmcnt(4)
	v_cvt_pk_bf16_f32 v3, v12, v14
	s_waitcnt lgkmcnt(2)
	v_cvt_pk_bf16_f32 v4, v16, v18
	s_waitcnt lgkmcnt(0)
	v_cvt_pk_bf16_f32 v5, v20, v24
	v_lshl_add_u64 v[6:7], v[22:23], 0, v[72:73]
	global_store_dwordx4 v[6:7], v[2:5], off
	v_or_b32_e32 v6, s4, v102
	v_lshlrev_b32_e32 v72, 12, v6
	v_cvt_pk_bf16_f32 v2, v9, v11
	v_cvt_pk_bf16_f32 v3, v13, v15
	v_cvt_pk_bf16_f32 v4, v17, v19
	v_cvt_pk_bf16_f32 v5, v21, v25
	ds_read2_b32 v[8:9], v77 offset0:48 offset1:56
	ds_read2_b32 v[10:11], v77 offset0:113 offset1:121
	ds_read2_b32 v[12:13], v77 offset0:178 offset1:186
	ds_read2_b32 v[14:15], v77 offset0:243 offset1:251
	ds_read2_b32 v[16:17], v26 offset0:52 offset1:60
	ds_read2_b32 v[18:19], v26 offset0:117 offset1:125
	ds_read2_b32 v[20:21], v26 offset0:182 offset1:190
	ds_read2_b32 v[24:25], v26 offset0:247 offset1:255
	v_lshl_add_u64 v[6:7], v[22:23], 0, v[72:73]
	global_store_dwordx4 v[6:7], v[2:5], off
	v_or_b32_e32 v6, s4, v103
	v_lshlrev_b32_e32 v72, 12, v6
	s_waitcnt lgkmcnt(6)
	v_cvt_pk_bf16_f32 v2, v8, v10
	s_waitcnt lgkmcnt(4)
	v_cvt_pk_bf16_f32 v3, v12, v14
	s_waitcnt lgkmcnt(2)
	v_cvt_pk_bf16_f32 v4, v16, v18
	s_waitcnt lgkmcnt(0)
	v_cvt_pk_bf16_f32 v5, v20, v24
	v_lshl_add_u64 v[6:7], v[22:23], 0, v[72:73]
	global_store_dwordx4 v[6:7], v[2:5], off
	v_or_b32_e32 v6, s4, v104
	v_lshlrev_b32_e32 v72, 12, v6
	v_cvt_pk_bf16_f32 v2, v9, v11
	v_cvt_pk_bf16_f32 v3, v13, v15
	v_cvt_pk_bf16_f32 v4, v17, v19
	v_cvt_pk_bf16_f32 v5, v21, v25
	v_lshl_add_u64 v[6:7], v[22:23], 0, v[72:73]
	global_store_dwordx4 v[6:7], v[2:5], off
	s_waitcnt lgkmcnt(0)

; #define LAS __attribute__((address_space(3)))
; #define FIN(i) ((const float*)(const GAS float*)(((const float* const __attribute__((address_space(4)))*)__builtin_amdgcn_kernarg_segment_ptr())[i]))
; template <class MAP>
; __device__ __forceinline__ void transpose_item(const float* W, int ldw, int K, bf16_t* WT, int k0, int nd0, LAS float* scr, int lane, const MAP& map) {
;     const int nq = 4 * (lane & 15), ns = map(nd0 + nq), kr = lane >> 4;
;     f32x4 v[16];
; #pragma unroll
;     for (int i = 0; i < 16; ++i) v[i] = ns >= 0 ? *(const f32x4*)(W + (size_t)(k0 + 4 * i + kr) * ldw + ns) : (f32x4){0.f, 0.f, 0.f, 0.f};
; #pragma unroll
;     for (int i = 0; i < 16; ++i) { LAS float* d = scr + (4 * i + kr) * 65 + nq; d[0] = v[i].x; d[1] = v[i].y; d[2] = v[i].z; d[3] = v[i].w; }
; __device__ __forceinline__ void phase_prologue(Frame& F) {
;     ...
;         if (r < 3 * I_BR) { const int z = r / I_BR, rr = r % I_BR, kb = rr / 32, nb = rr % 32;
;             const float* src = FIN(IN_WBRP + z) + (size_t)l * 1024 * 2048;
;             transpose_item(src, 2048, 1024, (bf16_t*)(F.ws + WS_WBR + l * al1m(SZ_WBR)) + (size_t)z * 2048 * 1024, 64 * kb, 64 * nb, scr, lane, MapId()); continue; } r -= 3 * I_BR;
.LBB0_24:
	s_andn2_b64 vcc, exec, s[4:5]
	s_cbranch_vccnz .LBB0_26
	s_add_i32 s4, s10, 0xffffe380
	s_lshr_b32 s6, s4, 9
	s_lshl_b32 s4, s6, 3
	s_load_dwordx2 s[4:5], s[0:1], s4 offset:0xb8
	s_ashr_i32 s9, s8, 31
	s_lshl_b64 s[62:63], s[8:9], 23
	s_mul_i32 s64, s8, 0xc00000
	s_mul_hi_i32 s11, s8, 0xc00000
	s_waitcnt lgkmcnt(0)
	s_add_u32 s62, s4, s62
	s_addc_u32 s63, s5, s63
	s_add_u32 s9, s19, s64
	s_addc_u32 s11, s20, s11
	s_lshl_b64 s[4:5], s[6:7], 22
	s_add_u32 s6, s9, s4
	s_mul_i32 s4, s8, 0xffffb180
	s_addc_u32 s5, s11, s5
	s_add_i32 s4, s29, s4
	s_addk_i32 s4, 0xc700
	s_and_b32 s9, s4, 0x3c0
	s_and_b32 s4, s25, 0x7c0
	v_or_b32_e32 v2, s4, v70
	v_or_b32_e32 v4, s9, v67
	v_lshlrev_b32_e32 v72, 2, v2
	v_lshl_add_u64 v[2:3], s[62:63], 0, v[72:73]
	v_lshlrev_b32_e32 v72, 13, v4
	v_lshl_add_u64 v[62:63], v[2:3], 0, v[72:73]
	v_add_co_u32_e32 v6, vcc, s39, v62
	s_lshl_b32 s9, s9, 1
	s_nop 0
	v_addc_co_u32_e32 v7, vcc, 0, v63, vcc
	v_add_co_u32_e32 v10, vcc, s44, v62
	global_load_dwordx4 v[2:5], v[62:63], off nt
	s_nop 0
	global_load_dwordx4 v[6:9], v[6:7], off nt
	v_addc_co_u32_e32 v11, vcc, 0, v63, vcc
	v_add_co_u32_e32 v14, vcc, s45, v62
	s_add_u32 s62, s6, s9
	s_nop 0
	v_addc_co_u32_e32 v15, vcc, 0, v63, vcc
	v_add_co_u32_e32 v18, vcc, s46, v62
	global_load_dwordx4 v[10:13], v[10:11], off nt
	s_nop 0
	global_load_dwordx4 v[14:17], v[14:15], off nt
	v_addc_co_u32_e32 v19, vcc, 0, v63, vcc
	v_add_co_u32_e32 v22, vcc, s47, v62
	s_addc_u32 s63, s5, 0
	s_nop 0
	v_addc_co_u32_e32 v23, vcc, 0, v63, vcc
	v_add_co_u32_e32 v26, vcc, s48, v62
	global_load_dwordx4 v[18:21], v[18:19], off nt
	s_nop 0
	global_load_dwordx4 v[22:25], v[22:23], off nt
	v_addc_co_u32_e32 v27, vcc, 0, v63, vcc
	v_add_co_u32_e32 v30, vcc, s49, v62
	v_lshlrev_b32_e32 v72, 1, v76
	s_nop 0
	v_addc_co_u32_e32 v31, vcc, 0, v63, vcc
	v_add_co_u32_e32 v34, vcc, s50, v62
	global_load_dwordx4 v[26:29], v[26:27], off nt
	s_nop 0
	global_load_dwordx4 v[30:33], v[30:31], off nt
	v_addc_co_u32_e32 v35, vcc, 0, v63, vcc
	v_add_co_u32_e32 v38, vcc, s51, v62
	s_nop 1
	v_addc_co_u32_e32 v39, vcc, 0, v63, vcc
	v_add_co_u32_e32 v42, vcc, s52, v62
	global_load_dwordx4 v[34:37], v[34:35], off nt
	s_nop 0
	global_load_dwordx4 v[38:41], v[38:39], off nt
	v_addc_co_u32_e32 v43, vcc, 0, v63, vcc
	v_add_co_u32_e32 v46, vcc, s53, v62
	s_nop 1
	v_addc_co_u32_e32 v47, vcc, 0, v63, vcc
	v_add_co_u32_e32 v50, vcc, s54, v62
	global_load_dwordx4 v[42:45], v[42:43], off nt
	s_nop 0
	global_load_dwordx4 v[46:49], v[46:47], off nt
	v_addc_co_u32_e32 v51, vcc, 0, v63, vcc
	global_load_dwordx4 v[50:53], v[50:51], off nt
	v_add_co_u32_e32 v54, vcc, s55, v62
	s_nop 1
	v_addc_co_u32_e32 v55, vcc, 0, v63, vcc
	global_load_dwordx4 v[54:57], v[54:55], off nt
	v_add_co_u32_e32 v58, vcc, s56, v62
	s_nop 1
	v_addc_co_u32_e32 v59, vcc, 0, v63, vcc
	global_load_dwordx4 v[58:61], v[58:59], off nt
	v_add_co_u32_e32 v62, vcc, s57, v62
	s_nop 1
	v_addc_co_u32_e32 v63, vcc, 0, v63, vcc
	global_load_dwordx4 v[62:65], v[62:63], off nt
	s_waitcnt vmcnt(15)
	ds_write2_b32 v69, v2, v3 offset1:1
	ds_write2_b32 v69, v4, v5 offset0:2 offset1:3
	s_waitcnt vmcnt(14)
	ds_write2_b32 v105, v6, v7 offset1:1
	ds_write2_b32 v106, v8, v9 offset1:1
	s_waitcnt vmcnt(13)
	ds_write2_b32 v107, v10, v11 offset1:1
	ds_write2_b32 v108, v12, v13 offset1:1
	s_waitcnt vmcnt(12)
	ds_write2_b32 v109, v14, v15 offset1:1
	ds_write2_b32 v110, v16, v17 offset1:1
	s_waitcnt vmcnt(11)
	ds_write2_b32 v111, v18, v19 offset1:1
	ds_write2_b32 v112, v20, v21 offset1:1
	s_waitcnt vmcnt(10)
	ds_write2_b32 v113, v22, v23 offset1:1
	ds_write2_b32 v114, v24, v25 offset1:1
	s_waitcnt vmcnt(9)
	ds_write2_b32 v115, v26, v27 offset1:1
	ds_write2_b32 v116, v28, v29 offset1:1
	s_waitcnt vmcnt(8)
	ds_write2_b32 v117, v30, v31 offset1:1
	ds_write2_b32 v118, v32, v33 offset1:1
	s_waitcnt vmcnt(7)
	ds_write2_b32 v119, v34, v35 offset1:1
	ds_write2_b32 v120, v36, v37 offset1:1
	s_waitcnt vmcnt(6)
	ds_write2_b32 v121, v38, v39 offset1:1
	ds_write2_b32 v122, v40, v41 offset1:1
	s_waitcnt vmcnt(5)
	ds_write2_b32 v123, v42, v43 offset1:1
	ds_write2_b32 v124, v44, v45 offset1:1
	s_waitcnt vmcnt(4)
	ds_write2_b32 v125, v46, v47 offset1:1
	ds_write2_b32 v126, v48, v49 offset1:1
	v_add_u32_e32 v2, 0x30c0, v69
	v_add_u32_e32 v26, 0x400, v77
	s_waitcnt vmcnt(3)
	ds_write2_b32 v2, v50, v51 offset1:1
	v_add_u32_e32 v2, 0x30c8, v69
	ds_write2_b32 v2, v52, v53 offset1:1
	v_add_u32_e32 v2, 0x34d0, v69
	v_lshl_add_u64 v[22:23], s[62:63], 0, v[72:73]
	s_waitcnt vmcnt(2)
; #define LAS __attribute__((address_space(3)))
; __device__ __forceinline__ unsigned pk2(float lo, float hi) { f32x2 v = {lo, hi}; bf16x2_t b = __builtin_convertvector(v, bf16x2_t); return __builtin_bit_cast(unsigned, b); }
; #define LDS_WAIT() asm volatile("s_waitcnt lgkmcnt(0)" ::: "memory")
; template <class MAP>
; __device__ __forceinline__ void transpose_item(const float* W, int ldw, int K, bf16_t* WT, int k0, int nd0, LAS float* scr, int lane, const MAP& map) {
;     ...
;     for (int i = 0; i < 16; ++i) { LAS float* d = scr + (4 * i + kr) * 65 + nq; d[0] = v[i].x; d[1] = v[i].y; d[2] = v[i].z; d[3] = v[i].w; }
;     LDS_WAIT(); asm volatile("" ::: "memory");
;     const int c = lane & 7;
; #pragma unroll
;     for (int j = 0; j < 8; ++j) { const int n = (lane >> 3) + 8 * j; const LAS float* s = scr + (8 * c) * 65 + n;
;         u32x4 o; o.x = pk2(s[0 * 65], s[1 * 65]); o.y = pk2(s[2 * 65], s[3 * 65]); o.z = pk2(s[4 * 65], s[5 * 65]); o.w = pk2(s[6 * 65], s[7 * 65]);
;         *(u32x4*)(WT + (size_t)(nd0 + n) * K + k0 + 8 * c) = o; }
;     LDS_WAIT(); asm volatile("" ::: "memory");
	ds_write2_b32 v2, v54, v55 offset1:1
	v_add_u32_e32 v2, 0x34d8, v69
	ds_write2_b32 v2, v56, v57 offset1:1
	v_add_u32_e32 v2, 0x38e0, v69
	s_waitcnt vmcnt(1)
	ds_write2_b32 v2, v58, v59 offset1:1
	v_add_u32_e32 v2, 0x38e8, v69
	ds_write2_b32 v2, v60, v61 offset1:1
	v_add_u32_e32 v2, 0x3cf0, v69
	s_waitcnt vmcnt(0)
	ds_write2_b32 v2, v62, v63 offset1:1
	v_add_u32_e32 v2, 0x3cf8, v69
	ds_write2_b32 v2, v64, v65 offset1:1
	s_waitcnt lgkmcnt(0)
	ds_read2_b32 v[6:7], v77 offset0:65 offset1:73
	ds_read2_b32 v[8:9], v77 offset1:8
	ds_read2_b32 v[10:11], v77 offset0:130 offset1:138
	ds_read2_b32 v[12:13], v77 offset0:195 offset1:203
	ds_read2_b32 v[14:15], v26 offset0:4 offset1:12
	ds_read2_b32 v[16:17], v26 offset0:69 offset1:77
	ds_read2_b32 v[18:19], v26 offset0:134 offset1:142
	ds_read2_b32 v[20:21], v26 offset0:199 offset1:207
	s_waitcnt lgkmcnt(6)
	v_cvt_pk_bf16_f32 v2, v8, v6
	v_or_b32_e32 v6, s4, v71
	v_lshlrev_b32_e32 v72, 11, v6
	s_waitcnt lgkmcnt(4)
	v_cvt_pk_bf16_f32 v3, v10, v12
	s_waitcnt lgkmcnt(2)
	v_cvt_pk_bf16_f32 v4, v14, v16
	s_waitcnt lgkmcnt(0)
	v_cvt_pk_bf16_f32 v5, v18, v20
	v_lshl_add_u64 v[24:25], v[22:23], 0, v[72:73]
	global_store_dwordx4 v[24:25], v[2:5], off
	v_or_b32_e32 v6, s4, v98
	v_lshlrev_b32_e32 v72, 11, v6
	v_cvt_pk_bf16_f32 v2, v9, v7
	v_cvt_pk_bf16_f32 v3, v11, v13
	v_cvt_pk_bf16_f32 v4, v15, v17
	v_cvt_pk_bf16_f32 v5, v19, v21
	ds_read2_b32 v[8:9], v77 offset0:81 offset1:89
	ds_read2_b32 v[10:11], v77 offset0:16 offset1:24
	ds_read2_b32 v[12:13], v77 offset0:146 offset1:154
	ds_read2_b32 v[14:15], v77 offset0:211 offset1:219
	ds_read2_b32 v[16:17], v26 offset0:20 offset1:28
	ds_read2_b32 v[18:19], v26 offset0:85 offset1:93
	ds_read2_b32 v[20:21], v26 offset0:150 offset1:158
	ds_read2_b32 v[24:25], v26 offset0:215 offset1:223
	v_lshl_add_u64 v[6:7], v[22:23], 0, v[72:73]
	global_store_dwordx4 v[6:7], v[2:5], off
	v_or_b32_e32 v6, s4, v99
	v_lshlrev_b32_e32 v72, 11, v6
	s_waitcnt lgkmcnt(6)
	v_cvt_pk_bf16_f32 v2, v10, v8
	s_waitcnt lgkmcnt(4)
	v_cvt_pk_bf16_f32 v3, v12, v14
	s_waitcnt lgkmcnt(2)
	v_cvt_pk_bf16_f32 v4, v16, v18
	s_waitcnt lgkmcnt(0)
	v_cvt_pk_bf16_f32 v5, v20, v24
	v_lshl_add_u64 v[6:7], v[22:23], 0, v[72:73]
	global_store_dwordx4 v[6:7], v[2:5], off
	v_or_b32_e32 v6, s4, v100
	v_lshlrev_b32_e32 v72, 11, v6
	v_cvt_pk_bf16_f32 v2, v11, v9
	v_cvt_pk_bf16_f32 v3, v13, v15
	v_cvt_pk_bf16_f32 v4, v17, v19
	v_cvt_pk_bf16_f32 v5, v21, v25
	ds_read2_b32 v[8:9], v77 offset0:32 offset1:40
	ds_read2_b32 v[10:11], v77 offset0:97 offset1:105
	ds_read2_b32 v[12:13], v77 offset0:162 offset1:170
	ds_read2_b32 v[14:15], v77 offset0:227 offset1:235
	ds_read2_b32 v[16:17], v26 offset0:36 offset1:44
	ds_read2_b32 v[18:19], v26 offset0:101 offset1:109
	ds_read2_b32 v[20:21], v26 offset0:166 offset1:174
	ds_read2_b32 v[24:25], v26 offset0:231 offset1:239
	v_lshl_add_u64 v[6:7], v[22:23], 0, v[72:73]
	global_store_dwordx4 v[6:7], v[2:5], off
	v_or_b32_e32 v6, s4, v101
	v_lshlrev_b32_e32 v72, 11, v6
	s_waitcnt lgkmcnt(6)
	v_cvt_pk_bf16_f32 v2, v8, v10
	s_waitcnt lgkmcnt(4)
	v_cvt_pk_bf16_f32 v3, v12, v14
	s_waitcnt lgkmcnt(2)
	v_cvt_pk_bf16_f32 v4, v16, v18
	s_waitcnt lgkmcnt(0)
	v_cvt_pk_bf16_f32 v5, v20, v24
	v_lshl_add_u64 v[6:7], v[22:23], 0, v[72:73]
	global_store_dwordx4 v[6:7], v[2:5], off
	v_or_b32_e32 v6, s4, v102
	v_lshlrev_b32_e32 v72, 11, v6
	v_cvt_pk_bf16_f32 v2, v9, v11
	v_cvt_pk_bf16_f32 v3, v13, v15
	v_cvt_pk_bf16_f32 v4, v17, v19
	v_cvt_pk_bf16_f32 v5, v21, v25
	ds_read2_b32 v[8:9], v77 offset0:48 offset1:56
	ds_read2_b32 v[10:11], v77 offset0:113 offset1:121
	ds_read2_b32 v[12:13], v77 offset0:178 offset1:186
	ds_read2_b32 v[14:15], v77 offset0:243 offset1:251
	ds_read2_b32 v[16:17], v26 offset0:52 offset1:60
	ds_read2_b32 v[18:19], v26 offset0:117 offset1:125
	ds_read2_b32 v[20:21], v26 offset0:182 offset1:190
	ds_read2_b32 v[24:25], v26 offset0:247 offset1:255
	v_lshl_add_u64 v[6:7], v[22:23], 0, v[72:73]
	global_store_dwordx4 v[6:7], v[2:5], off
	v_or_b32_e32 v6, s4, v103
	v_lshlrev_b32_e32 v72, 11, v6
	s_waitcnt lgkmcnt(6)
	v_cvt_pk_bf16_f32 v2, v8, v10
	s_waitcnt lgkmcnt(4)
	v_cvt_pk_bf16_f32 v3, v12, v14
	s_waitcnt lgkmcnt(2)
	v_cvt_pk_bf16_f32 v4, v16, v18
	s_waitcnt lgkmcnt(0)
	v_cvt_pk_bf16_f32 v5, v20, v24
	v_lshl_add_u64 v[6:7], v[22:23], 0, v[72:73]
	global_store_dwordx4 v[6:7], v[2:5], off
	v_or_b32_e32 v6, s4, v104
	v_lshlrev_b32_e32 v72, 11, v6
	v_cvt_pk_bf16_f32 v2, v9, v11
	v_cvt_pk_bf16_f32 v3, v13, v15
	v_cvt_pk_bf16_f32 v4, v17, v19
	v_cvt_pk_bf16_f32 v5, v21, v25
	v_lshl_add_u64 v[6:7], v[22:23], 0, v[72:73]
	global_store_dwordx4 v[6:7], v[2:5], off
	s_waitcnt lgkmcnt(0)

; #define LAS __attribute__((address_space(3)))
; #define FIN(i) ((const float*)(const GAS float*)(((const float* const __attribute__((address_space(4)))*)__builtin_amdgcn_kernarg_segment_ptr())[i]))
; template <class MAP>
; __device__ __forceinline__ void transpose_item(const float* W, int ldw, int K, bf16_t* WT, int k0, int nd0, LAS float* scr, int lane, const MAP& map) {
;     const int nq = 4 * (lane & 15), ns = map(nd0 + nq), kr = lane >> 4;
;     f32x4 v[16];
; #pragma unroll
;     for (int i = 0; i < 16; ++i) v[i] = ns >= 0 ? *(const f32x4*)(W + (size_t)(k0 + 4 * i + kr) * ldw + ns) : (f32x4){0.f, 0.f, 0.f, 0.f};
; #pragma unroll
;     for (int i = 0; i < 16; ++i) { LAS float* d = scr + (4 * i + kr) * 65 + nq; d[0] = v[i].x; d[1] = v[i].y; d[2] = v[i].z; d[3] = v[i].w; }
; __device__ __forceinline__ void phase_prologue(Frame& F) {
;     ...
;         if (r < I_GLU) { const int kb = r / 16, nb = r % 16;
;             transpose_item(FIN(IN_WGLU) + (size_t)l * 1024 * 1024, 1024, 1024, (bf16_t*)(F.ws + WS_WGLU + l * al1m(SZ_WGLU)), 64 * kb, 64 * nb, scr, lane, MapId()); continue; } r -= I_GLU;
.LBB0_27:
	s_andn2_b64 vcc, exec, s[4:5]
	s_cbranch_vccnz .LBB0_29
	s_load_dwordx2 s[4:5], s[0:1], 0xb0
	s_ashr_i32 s9, s8, 31
	s_lshl_b64 s[62:63], s[8:9], 22
	s_mul_i32 s6, s8, 0xffff6300
	v_mov_b32_e32 v63, v73
	s_waitcnt lgkmcnt(0)
	s_add_u32 s62, s4, s62
	s_addc_u32 s63, s5, s63
	s_lshl_b64 s[4:5], s[8:9], 21
	s_add_u32 s9, s21, s4
	s_addc_u32 s5, s22, s5
	s_add_i32 s4, s27, s6
	s_and_b32 s4, s4, 0x7fc0
	s_add_i32 s6, s4, 0xffff9200
	s_and_b32 s4, s25, 0x3c0
	v_or_b32_e32 v2, s4, v70
	v_or_b32_e32 v62, s6, v67
	v_lshlrev_b32_e32 v72, 2, v2
	v_lshl_add_u64 v[64:65], s[62:63], 0, v[72:73]
	v_or_b32_e32 v72, 4, v62
	v_lshlrev_b64 v[4:5], 12, v[72:73]
	v_or_b32_e32 v72, 8, v62
	v_lshlrev_b64 v[10:11], 12, v[72:73]
	v_or_b32_e32 v72, 12, v62
	v_lshlrev_b64 v[12:13], 12, v[72:73]
	v_or_b32_e32 v72, 16, v62
	v_lshlrev_b64 v[18:19], 12, v[72:73]
	v_or_b32_e32 v72, 20, v62
	v_lshlrev_b64 v[20:21], 12, v[72:73]
	v_or_b32_e32 v72, 24, v62
	v_lshlrev_b64 v[26:27], 12, v[72:73]
	v_or_b32_e32 v72, 28, v62
	v_lshlrev_b64 v[28:29], 12, v[72:73]
	v_or_b32_e32 v72, 32, v62
	v_lshlrev_b64 v[34:35], 12, v[72:73]
	v_or_b32_e32 v72, 36, v62
	v_lshlrev_b64 v[36:37], 12, v[72:73]
	v_or_b32_e32 v72, 40, v62
	v_lshlrev_b64 v[42:43], 12, v[72:73]
	v_or_b32_e32 v72, 44, v62
	v_lshlrev_b64 v[2:3], 12, v[62:63]
	v_lshlrev_b64 v[44:45], 12, v[72:73]
	v_or_b32_e32 v72, 48, v62
	v_lshl_add_u64 v[2:3], v[64:65], 0, v[2:3]
	v_lshl_add_u64 v[6:7], v[64:65], 0, v[4:5]
	v_lshl_add_u64 v[10:11], v[64:65], 0, v[10:11]
	v_lshl_add_u64 v[14:15], v[64:65], 0, v[12:13]
	v_lshl_add_u64 v[18:19], v[64:65], 0, v[18:19]
	v_lshl_add_u64 v[22:23], v[64:65], 0, v[20:21]
	v_lshl_add_u64 v[26:27], v[64:65], 0, v[26:27]
	v_lshl_add_u64 v[30:31], v[64:65], 0, v[28:29]
	v_lshl_add_u64 v[34:35], v[64:65], 0, v[34:35]
	v_lshl_add_u64 v[38:39], v[64:65], 0, v[36:37]
	v_lshl_add_u64 v[42:43], v[64:65], 0, v[42:43]
	v_lshl_add_u64 v[46:47], v[64:65], 0, v[44:45]
	v_lshlrev_b64 v[50:51], 12, v[72:73]
	v_or_b32_e32 v72, 52, v62
	global_load_dwordx4 v[2:5], v[2:3], off nt
	s_nop 0
	global_load_dwordx4 v[6:9], v[6:7], off nt
	s_nop 0
	global_load_dwordx4 v[10:13], v[10:11], off nt
	s_nop 0
	global_load_dwordx4 v[14:17], v[14:15], off nt
	s_nop 0
	global_load_dwordx4 v[18:21], v[18:19], off nt
	s_nop 0
	global_load_dwordx4 v[22:25], v[22:23], off nt
	s_nop 0
	global_load_dwordx4 v[26:29], v[26:27], off nt
	s_nop 0
	global_load_dwordx4 v[30:33], v[30:31], off nt
	s_nop 0
	global_load_dwordx4 v[34:37], v[34:35], off nt
	s_nop 0
	global_load_dwordx4 v[38:41], v[38:39], off nt
	s_nop 0
	global_load_dwordx4 v[42:45], v[42:43], off nt
	s_nop 0
	global_load_dwordx4 v[46:49], v[46:47], off nt
	v_lshl_add_u64 v[50:51], v[64:65], 0, v[50:51]
	v_lshlrev_b64 v[54:55], 12, v[72:73]
	global_load_dwordx4 v[50:53], v[50:51], off nt
	v_lshl_add_u64 v[54:55], v[64:65], 0, v[54:55]
	v_or_b32_e32 v72, 56, v62
	global_load_dwordx4 v[54:57], v[54:55], off nt
	v_lshlrev_b64 v[58:59], 12, v[72:73]
	v_lshl_add_u64 v[58:59], v[64:65], 0, v[58:59]
	v_or_b32_e32 v72, 60, v62
	global_load_dwordx4 v[58:61], v[58:59], off nt
	v_lshlrev_b64 v[62:63], 12, v[72:73]
	v_lshl_add_u64 v[62:63], v[64:65], 0, v[62:63]
	global_load_dwordx4 v[62:65], v[62:63], off nt
	v_add_u32_e32 v72, 0x30c0, v69
	s_lshl_b64 s[62:63], s[6:7], 1
	s_add_u32 s62, s9, s62
	s_addc_u32 s63, s5, s63
	s_waitcnt vmcnt(15)
	ds_write2_b32 v69, v2, v3 offset1:1
	ds_write2_b32 v69, v4, v5 offset0:2 offset1:3
	s_waitcnt vmcnt(14)
	ds_write2_b32 v105, v6, v7 offset1:1
	ds_write2_b32 v106, v8, v9 offset1:1
	s_waitcnt vmcnt(13)
	ds_write2_b32 v107, v10, v11 offset1:1
	ds_write2_b32 v108, v12, v13 offset1:1
	s_waitcnt vmcnt(12)
	ds_write2_b32 v109, v14, v15 offset1:1
	ds_write2_b32 v110, v16, v17 offset1:1
	s_waitcnt vmcnt(11)
	ds_write2_b32 v111, v18, v19 offset1:1
	ds_write2_b32 v112, v20, v21 offset1:1
	s_waitcnt vmcnt(10)
	ds_write2_b32 v113, v22, v23 offset1:1
	ds_write2_b32 v114, v24, v25 offset1:1
	s_waitcnt vmcnt(9)
	ds_write2_b32 v115, v26, v27 offset1:1
	ds_write2_b32 v116, v28, v29 offset1:1
	s_waitcnt vmcnt(8)
	ds_write2_b32 v117, v30, v31 offset1:1
	ds_write2_b32 v118, v32, v33 offset1:1
	s_waitcnt vmcnt(7)
	ds_write2_b32 v119, v34, v35 offset1:1
	ds_write2_b32 v120, v36, v37 offset1:1
	s_waitcnt vmcnt(6)
	ds_write2_b32 v121, v38, v39 offset1:1
	ds_write2_b32 v122, v40, v41 offset1:1
	s_waitcnt vmcnt(5)
	ds_write2_b32 v123, v42, v43 offset1:1
	ds_write2_b32 v124, v44, v45 offset1:1
	s_waitcnt vmcnt(4)
	ds_write2_b32 v125, v46, v47 offset1:1
	ds_write2_b32 v126, v48, v49 offset1:1
	s_waitcnt vmcnt(3)
	ds_write2_b32 v72, v50, v51 offset1:1
	v_add_u32_e32 v2, 0x30c8, v69
	v_add_u32_e32 v26, 0x400, v77
	ds_write2_b32 v2, v52, v53 offset1:1
	v_add_u32_e32 v2, 0x34d0, v69
	v_lshlrev_b32_e32 v72, 1, v76
	s_waitcnt vmcnt(2)
; #define LAS __attribute__((address_space(3)))
; __device__ __forceinline__ unsigned pk2(float lo, float hi) { f32x2 v = {lo, hi}; bf16x2_t b = __builtin_convertvector(v, bf16x2_t); return __builtin_bit_cast(unsigned, b); }
; #define LDS_WAIT() asm volatile("s_waitcnt lgkmcnt(0)" ::: "memory")
; template <class MAP>
; __device__ __forceinline__ void transpose_item(const float* W, int ldw, int K, bf16_t* WT, int k0, int nd0, LAS float* scr, int lane, const MAP& map) {
;     ...
;     for (int i = 0; i < 16; ++i) { LAS float* d = scr + (4 * i + kr) * 65 + nq; d[0] = v[i].x; d[1] = v[i].y; d[2] = v[i].z; d[3] = v[i].w; }
;     LDS_WAIT(); asm volatile("" ::: "memory");
;     const int c = lane & 7;
; #pragma unroll
;     for (int j = 0; j < 8; ++j) { const int n = (lane >> 3) + 8 * j; const LAS float* s = scr + (8 * c) * 65 + n;
;         u32x4 o; o.x = pk2(s[0 * 65], s[1 * 65]); o.y = pk2(s[2 * 65], s[3 * 65]); o.z = pk2(s[4 * 65], s[5 * 65]); o.w = pk2(s[6 * 65], s[7 * 65]);
;         *(u32x4*)(WT + (size_t)(nd0 + n) * K + k0 + 8 * c) = o; }
;     LDS_WAIT(); asm volatile("" ::: "memory");
	ds_write2_b32 v2, v54, v55 offset1:1
	v_add_u32_e32 v2, 0x34d8, v69
	ds_write2_b32 v2, v56, v57 offset1:1
	v_add_u32_e32 v2, 0x38e0, v69
	s_waitcnt vmcnt(1)
	ds_write2_b32 v2, v58, v59 offset1:1
	v_add_u32_e32 v2, 0x38e8, v69
	ds_write2_b32 v2, v60, v61 offset1:1
	v_add_u32_e32 v2, 0x3cf0, v69
	s_waitcnt vmcnt(0)
	ds_write2_b32 v2, v62, v63 offset1:1
	v_add_u32_e32 v2, 0x3cf8, v69
	ds_write2_b32 v2, v64, v65 offset1:1
	s_waitcnt lgkmcnt(0)
	ds_read2_b32 v[6:7], v77 offset0:65 offset1:73
	ds_read2_b32 v[8:9], v77 offset1:8
	ds_read2_b32 v[10:11], v77 offset0:130 offset1:138
	ds_read2_b32 v[12:13], v77 offset0:195 offset1:203
	ds_read2_b32 v[14:15], v26 offset0:4 offset1:12
	ds_read2_b32 v[16:17], v26 offset0:69 offset1:77
	ds_read2_b32 v[18:19], v26 offset0:134 offset1:142
	ds_read2_b32 v[20:21], v26 offset0:199 offset1:207
	v_lshl_add_u64 v[22:23], s[62:63], 0, v[72:73]
	s_waitcnt lgkmcnt(6)
	v_cvt_pk_bf16_f32 v2, v8, v6
	v_or_b32_e32 v6, s4, v71
	v_lshlrev_b32_e32 v72, 11, v6
	s_waitcnt lgkmcnt(4)
	v_cvt_pk_bf16_f32 v3, v10, v12
	s_waitcnt lgkmcnt(2)
	v_cvt_pk_bf16_f32 v4, v14, v16
	s_waitcnt lgkmcnt(0)
	v_cvt_pk_bf16_f32 v5, v18, v20
	v_lshl_add_u64 v[24:25], v[22:23], 0, v[72:73]
	global_store_dwordx4 v[24:25], v[2:5], off
	v_or_b32_e32 v6, s4, v98
	v_lshlrev_b32_e32 v72, 11, v6
	v_cvt_pk_bf16_f32 v2, v9, v7
	v_cvt_pk_bf16_f32 v3, v11, v13
	v_cvt_pk_bf16_f32 v4, v15, v17
	v_cvt_pk_bf16_f32 v5, v19, v21
	ds_read2_b32 v[8:9], v77 offset0:81 offset1:89
	ds_read2_b32 v[10:11], v77 offset0:16 offset1:24
	ds_read2_b32 v[12:13], v77 offset0:146 offset1:154
	ds_read2_b32 v[14:15], v77 offset0:211 offset1:219
	ds_read2_b32 v[16:17], v26 offset0:20 offset1:28
	ds_read2_b32 v[18:19], v26 offset0:85 offset1:93
	ds_read2_b32 v[20:21], v26 offset0:150 offset1:158
	ds_read2_b32 v[24:25], v26 offset0:215 offset1:223
	v_lshl_add_u64 v[6:7], v[22:23], 0, v[72:73]
	global_store_dwordx4 v[6:7], v[2:5], off
	v_or_b32_e32 v6, s4, v99
	v_lshlrev_b32_e32 v72, 11, v6
	s_waitcnt lgkmcnt(6)
	v_cvt_pk_bf16_f32 v2, v10, v8
	s_waitcnt lgkmcnt(4)
	v_cvt_pk_bf16_f32 v3, v12, v14
	s_waitcnt lgkmcnt(2)
	v_cvt_pk_bf16_f32 v4, v16, v18
	s_waitcnt lgkmcnt(0)
	v_cvt_pk_bf16_f32 v5, v20, v24
	v_lshl_add_u64 v[6:7], v[22:23], 0, v[72:73]
	global_store_dwordx4 v[6:7], v[2:5], off
	v_or_b32_e32 v6, s4, v100
	v_lshlrev_b32_e32 v72, 11, v6
	v_cvt_pk_bf16_f32 v2, v11, v9
	v_cvt_pk_bf16_f32 v3, v13, v15
	v_cvt_pk_bf16_f32 v4, v17, v19
	v_cvt_pk_bf16_f32 v5, v21, v25
	ds_read2_b32 v[8:9], v77 offset0:32 offset1:40
	ds_read2_b32 v[10:11], v77 offset0:97 offset1:105
	ds_read2_b32 v[12:13], v77 offset0:162 offset1:170
	ds_read2_b32 v[14:15], v77 offset0:227 offset1:235
	ds_read2_b32 v[16:17], v26 offset0:36 offset1:44
	ds_read2_b32 v[18:19], v26 offset0:101 offset1:109
	ds_read2_b32 v[20:21], v26 offset0:166 offset1:174
	ds_read2_b32 v[24:25], v26 offset0:231 offset1:239
	v_lshl_add_u64 v[6:7], v[22:23], 0, v[72:73]
	global_store_dwordx4 v[6:7], v[2:5], off
	v_or_b32_e32 v6, s4, v101
	v_lshlrev_b32_e32 v72, 11, v6
	s_waitcnt lgkmcnt(6)
	v_cvt_pk_bf16_f32 v2, v8, v10
	s_waitcnt lgkmcnt(4)
	v_cvt_pk_bf16_f32 v3, v12, v14
	s_waitcnt lgkmcnt(2)
	v_cvt_pk_bf16_f32 v4, v16, v18
	s_waitcnt lgkmcnt(0)
	v_cvt_pk_bf16_f32 v5, v20, v24
	v_lshl_add_u64 v[6:7], v[22:23], 0, v[72:73]
	global_store_dwordx4 v[6:7], v[2:5], off
	v_or_b32_e32 v6, s4, v102
	v_lshlrev_b32_e32 v72, 11, v6
	v_cvt_pk_bf16_f32 v2, v9, v11
	v_cvt_pk_bf16_f32 v3, v13, v15
	v_cvt_pk_bf16_f32 v4, v17, v19
	v_cvt_pk_bf16_f32 v5, v21, v25
	ds_read2_b32 v[8:9], v77 offset0:48 offset1:56
	ds_read2_b32 v[10:11], v77 offset0:113 offset1:121
	ds_read2_b32 v[12:13], v77 offset0:178 offset1:186
	ds_read2_b32 v[14:15], v77 offset0:243 offset1:251
	ds_read2_b32 v[16:17], v26 offset0:52 offset1:60
	ds_read2_b32 v[18:19], v26 offset0:117 offset1:125
	ds_read2_b32 v[20:21], v26 offset0:182 offset1:190
	ds_read2_b32 v[24:25], v26 offset0:247 offset1:255
	v_lshl_add_u64 v[6:7], v[22:23], 0, v[72:73]
	global_store_dwordx4 v[6:7], v[2:5], off
	v_or_b32_e32 v6, s4, v103
	v_lshlrev_b32_e32 v72, 11, v6
	s_waitcnt lgkmcnt(6)
	v_cvt_pk_bf16_f32 v2, v8, v10
	s_waitcnt lgkmcnt(4)
	v_cvt_pk_bf16_f32 v3, v12, v14
	s_waitcnt lgkmcnt(2)
	v_cvt_pk_bf16_f32 v4, v16, v18
	s_waitcnt lgkmcnt(0)
	v_cvt_pk_bf16_f32 v5, v20, v24
	v_lshl_add_u64 v[6:7], v[22:23], 0, v[72:73]
	global_store_dwordx4 v[6:7], v[2:5], off
	v_or_b32_e32 v6, s4, v104
	v_lshlrev_b32_e32 v72, 11, v6
	v_cvt_pk_bf16_f32 v2, v9, v11
	v_cvt_pk_bf16_f32 v3, v13, v15
	v_cvt_pk_bf16_f32 v4, v17, v19
	v_cvt_pk_bf16_f32 v5, v21, v25
	v_lshl_add_u64 v[6:7], v[22:23], 0, v[72:73]
	global_store_dwordx4 v[6:7], v[2:5], off
	s_waitcnt lgkmcnt(0)

; #define LAS __attribute__((address_space(3)))
; #define FIN(i) ((const float*)(const GAS float*)(((const float* const __attribute__((address_space(4)))*)__builtin_amdgcn_kernarg_segment_ptr())[i]))
; template <class MAP>
; __device__ __forceinline__ void transpose_item(const float* W, int ldw, int K, bf16_t* WT, int k0, int nd0, LAS float* scr, int lane, const MAP& map) {
;     const int nq = 4 * (lane & 15), ns = map(nd0 + nq), kr = lane >> 4;
;     f32x4 v[16];
; #pragma unroll
;     for (int i = 0; i < 16; ++i) v[i] = ns >= 0 ? *(const f32x4*)(W + (size_t)(k0 + 4 * i + kr) * ldw + ns) : (f32x4){0.f, 0.f, 0.f, 0.f};
; __device__ __forceinline__ void phase_prologue(Frame& F) {
;     ...
;         if (r < I_WIN) { const int kb = r / (NPROJ / 64), nb = r % (NPROJ / 64);
;             transpose_item(FIN(IN_WIN) + (size_t)l * DM * DIN, DIN, DM, (bf16_t*)(F.ws + WS_WIN + l * al1m(SZ_WIN)), 64 * kb, 64 * nb, scr, lane, MapWin()); continue; } r -= I_WIN;
.LBB0_37:
	s_or_b64 exec, exec, s[4:5]
	s_load_dwordx2 s[4:5], s[0:1], 0x48
	s_mul_i32 s10, s8, 0x6c60000
	s_sext_i32_i16 s9, s9
	s_mul_hi_i32 s11, s8, 0x6c60000
	v_cmp_lt_i32_e32 vcc, -1, v72
	s_waitcnt lgkmcnt(0)
	s_add_u32 s10, s4, s10
	s_addc_u32 s11, s5, s11
	s_lshl_b32 s4, s9, 6
	v_or_b32_e32 v95, s4, v67
	v_lshl_add_u64 v[96:97], v[72:73], 2, s[10:11]
	v_mov_b32_e32 v2, 0
	v_mov_b32_e32 v6, 0
	v_mov_b32_e32 v7, 0
	v_mov_b32_e32 v8, 0
	v_mov_b32_e32 v9, 0
	s_and_saveexec_b64 s[10:11], vcc
	s_cbranch_execz .LBB0_39
	v_mul_i32_i24_e32 v4, 0xd8c0, v95
	v_ashrrev_i32_e32 v5, 31, v4
	v_lshl_add_u64 v[4:5], v[96:97], 0, v[4:5]
	global_load_dwordx4 v[6:9], v[4:5], off nt
.LBB0_39:
	s_or_b64 exec, exec, s[10:11]
	v_mov_b32_e32 v3, 0
	v_mov_b32_e32 v4, 0
	v_mov_b32_e32 v5, 0
	s_and_saveexec_b64 s[10:11], vcc
	s_cbranch_execz .LBB0_41
	v_mad_i32_i24 v2, v95, s60, v127
	v_ashrrev_i32_e32 v3, 31, v2
	v_lshl_add_u64 v[2:3], v[96:97], 0, v[2:3]
	global_load_dwordx4 v[2:5], v[2:3], off nt
.LBB0_41:
	s_or_b64 exec, exec, s[10:11]
	v_mov_b32_e32 v10, 0
	v_mov_b32_e32 v14, 0
	v_mov_b32_e32 v15, 0
	v_mov_b32_e32 v16, 0
	v_mov_b32_e32 v17, 0
	s_and_saveexec_b64 s[10:11], vcc
	s_cbranch_execz .LBB0_43
	v_mad_i32_i24 v12, v95, s60, v128
	v_ashrrev_i32_e32 v13, 31, v12
	v_lshl_add_u64 v[12:13], v[96:97], 0, v[12:13]
	global_load_dwordx4 v[14:17], v[12:13], off nt
.LBB0_43:
	s_or_b64 exec, exec, s[10:11]
	v_mov_b32_e32 v11, 0
	v_mov_b32_e32 v12, 0
	v_mov_b32_e32 v13, 0
	s_and_saveexec_b64 s[10:11], vcc
	s_cbranch_execz .LBB0_45
	v_mad_i32_i24 v10, v95, s60, v129
	v_ashrrev_i32_e32 v11, 31, v10
	v_lshl_add_u64 v[10:11], v[96:97], 0, v[10:11]
	global_load_dwordx4 v[10:13], v[10:11], off nt
.LBB0_45:
	s_or_b64 exec, exec, s[10:11]
	v_mov_b32_e32 v18, 0
	v_mov_b32_e32 v22, 0
	v_mov_b32_e32 v23, 0
	v_mov_b32_e32 v24, 0
	v_mov_b32_e32 v25, 0
	s_and_saveexec_b64 s[10:11], vcc
	s_cbranch_execz .LBB0_47
	v_mad_i32_i24 v20, v95, s60, v130
	v_ashrrev_i32_e32 v21, 31, v20
	v_lshl_add_u64 v[20:21], v[96:97], 0, v[20:21]
	global_load_dwordx4 v[22:25], v[20:21], off nt
.LBB0_47:
	s_or_b64 exec, exec, s[10:11]
	v_mov_b32_e32 v19, 0
	v_mov_b32_e32 v20, 0
	v_mov_b32_e32 v21, 0
	s_and_saveexec_b64 s[10:11], vcc
	s_cbranch_execz .LBB0_49
	v_mad_i32_i24 v18, v95, s60, v131
	v_ashrrev_i32_e32 v19, 31, v18
	v_lshl_add_u64 v[18:19], v[96:97], 0, v[18:19]
	global_load_dwordx4 v[18:21], v[18:19], off nt
.LBB0_49:
	s_or_b64 exec, exec, s[10:11]
	v_mov_b32_e32 v26, 0
	v_mov_b32_e32 v30, 0
	v_mov_b32_e32 v31, 0
	v_mov_b32_e32 v32, 0
	v_mov_b32_e32 v33, 0
	s_and_saveexec_b64 s[10:11], vcc
	s_cbranch_execz .LBB0_51
	v_mad_i32_i24 v28, v95, s60, v132
	v_ashrrev_i32_e32 v29, 31, v28
	v_lshl_add_u64 v[28:29], v[96:97], 0, v[28:29]
	global_load_dwordx4 v[30:33], v[28:29], off nt
.LBB0_51:
	s_or_b64 exec, exec, s[10:11]
	v_mov_b32_e32 v27, 0
	v_mov_b32_e32 v28, 0
	v_mov_b32_e32 v29, 0
	s_and_saveexec_b64 s[10:11], vcc
	s_cbranch_execz .LBB0_53
	v_mad_i32_i24 v26, v95, s60, v133
	v_ashrrev_i32_e32 v27, 31, v26
	v_lshl_add_u64 v[26:27], v[96:97], 0, v[26:27]
	global_load_dwordx4 v[26:29], v[26:27], off nt
.LBB0_53:
	s_or_b64 exec, exec, s[10:11]
	v_mov_b32_e32 v34, 0
	v_mov_b32_e32 v38, 0
	v_mov_b32_e32 v39, 0
	v_mov_b32_e32 v40, 0
	v_mov_b32_e32 v41, 0
	s_and_saveexec_b64 s[10:11], vcc
	s_cbranch_execz .LBB0_55
	v_mad_i32_i24 v36, v95, s60, v134
	v_ashrrev_i32_e32 v37, 31, v36
	v_lshl_add_u64 v[36:37], v[96:97], 0, v[36:37]
	global_load_dwordx4 v[38:41], v[36:37], off nt
.LBB0_55:
	s_or_b64 exec, exec, s[10:11]
	v_mov_b32_e32 v35, 0
	v_mov_b32_e32 v36, 0
	v_mov_b32_e32 v37, 0
	s_and_saveexec_b64 s[10:11], vcc
	s_cbranch_execz .LBB0_57
	v_mad_i32_i24 v34, v95, s60, v135
	v_ashrrev_i32_e32 v35, 31, v34
	v_lshl_add_u64 v[34:35], v[96:97], 0, v[34:35]
	global_load_dwordx4 v[34:37], v[34:35], off nt
.LBB0_57:
	s_or_b64 exec, exec, s[10:11]
	v_mov_b32_e32 v42, 0
	v_mov_b32_e32 v46, 0
	v_mov_b32_e32 v47, 0
	v_mov_b32_e32 v48, 0
	v_mov_b32_e32 v49, 0
	s_and_saveexec_b64 s[10:11], vcc
	s_cbranch_execz .LBB0_59
	v_mad_i32_i24 v44, v95, s60, v136
	v_ashrrev_i32_e32 v45, 31, v44
	v_lshl_add_u64 v[44:45], v[96:97], 0, v[44:45]
	global_load_dwordx4 v[46:49], v[44:45], off nt
.LBB0_59:
	s_or_b64 exec, exec, s[10:11]
	v_mov_b32_e32 v43, 0
	v_mov_b32_e32 v44, 0
	v_mov_b32_e32 v45, 0
	s_and_saveexec_b64 s[10:11], vcc
	s_cbranch_execz .LBB0_61
	v_mad_i32_i24 v42, v95, s60, v137
	v_ashrrev_i32_e32 v43, 31, v42
	v_lshl_add_u64 v[42:43], v[96:97], 0, v[42:43]
	global_load_dwordx4 v[42:45], v[42:43], off nt
.LBB0_61:
	s_or_b64 exec, exec, s[10:11]
	v_mov_b32_e32 v50, 0
	v_mov_b32_e32 v54, 0
	v_mov_b32_e32 v55, 0
	v_mov_b32_e32 v56, 0
	v_mov_b32_e32 v57, 0
	s_and_saveexec_b64 s[10:11], vcc
	s_cbranch_execz .LBB0_63
	v_mad_i32_i24 v52, v95, s60, v138
	v_ashrrev_i32_e32 v53, 31, v52
	v_lshl_add_u64 v[52:53], v[96:97], 0, v[52:53]
	global_load_dwordx4 v[54:57], v[52:53], off nt
.LBB0_63:
	s_or_b64 exec, exec, s[10:11]
	v_mov_b32_e32 v51, 0
	v_mov_b32_e32 v52, 0
	v_mov_b32_e32 v53, 0
	s_and_saveexec_b64 s[10:11], vcc
	s_cbranch_execz .LBB0_65
	v_mad_i32_i24 v50, v95, s60, v139
	v_ashrrev_i32_e32 v51, 31, v50
	v_lshl_add_u64 v[50:51], v[96:97], 0, v[50:51]
	global_load_dwordx4 v[50:53], v[50:51], off nt
.LBB0_65:
	s_or_b64 exec, exec, s[10:11]
	v_mov_b32_e32 v58, 0
	v_mov_b32_e32 v62, 0
	v_mov_b32_e32 v63, 0
	v_mov_b32_e32 v64, 0
	v_mov_b32_e32 v65, 0
	s_and_saveexec_b64 s[10:11], vcc
	s_cbranch_execz .LBB0_67
	v_mad_i32_i24 v60, v95, s60, v140
	v_ashrrev_i32_e32 v61, 31, v60
	v_lshl_add_u64 v[60:61], v[96:97], 0, v[60:61]
	global_load_dwordx4 v[62:65], v[60:61], off nt
.LBB0_67:
	s_or_b64 exec, exec, s[10:11]
	v_mov_b32_e32 v59, 0
	v_mov_b32_e32 v60, 0
	v_mov_b32_e32 v61, 0
	s_and_saveexec_b64 s[10:11], vcc
	s_cbranch_execz .LBB0_10
	v_mad_i32_i24 v58, v95, s60, v141
	v_ashrrev_i32_e32 v59, 31, v58
	v_lshl_add_u64 v[58:59], v[96:97], 0, v[58:59]
	global_load_dwordx4 v[58:61], v[58:59], off nt
	s_branch .LBB0_10
